# next-unit queue index fetched at the start of each attention unit's epilogue (prompt and memory-attention queues) instead of a serial atomic round trip at the next unit's head
# speedup vs baseline: 1.0036x; 1.0036x over previous
.LBB0_444:
	v_readlane_b32 s0, v253, 27
	v_mov_b32_e32 v187, v186
	v_mov_b32_e32 v222, -1
	s_mov_b32 s36, s0
	s_branch .LBB0_446

.LBB0_446:
	v_mov_b32_e32 v0, v204
	s_barrier
	s_nop 0
	v_cmp_eq_u32_e32 vcc, 0, v0
	s_and_saveexec_b64 s[0:1], vcc
	s_cbranch_execz .LBB0_450
	s_waitcnt vmcnt(0)
	v_readfirstlane_b32 s19, v222
	v_mov_b32_e32 v222, -1
	v_mov_b32_e32 v0, 0
	s_cmp_eq_u32 s19, -1
	s_cbranch_scc0 .Lpf_have
	s_mov_b64 s[42:43], exec
	v_mbcnt_lo_u32_b32 v0, s42, 0
	v_mbcnt_hi_u32_b32 v0, s43, v0
	v_cmp_eq_u32_e32 vcc, 0, v0
	s_and_saveexec_b64 s[38:39], vcc
	s_cbranch_execz .LBB0_449
	s_mov_b32 s37, s73
	s_lshl_b64 s[20:21], s[36:37], 2
	s_add_u32 s20, s74, s20
	s_addc_u32 s21, s75, s21
	s_bcnt1_i32_b64 s19, s[42:43]
	v_mov_b32_e32 v2, s19
	global_atomic_add v2, v1, v2, s[20:21] sc0

.Lpf_have:
	v_mov_b32_e32 v2, s10
	s_nop 0
	v_add_u32_e32 v0, s19, v0
	ds_write_b32 v2, v0

.Lsp_epi:
	ds_bpermute_b32 v2, v225, v232
	s_waitcnt vmcnt(0)
	v_cmp_eq_u32_e32 vcc, 0, v204
	s_and_saveexec_b64 s[98:99], vcc
	s_cbranch_execz .Lpf_skip
	s_lshl_b32 s100, s36, 2
	s_add_u32 s100, s74, s100
	s_addc_u32 s101, s75, 0
	v_mov_b32_e32 v222, 1
	global_atomic_add v222, v1, v222, s[100:101] sc0
.Lpf_skip:
	s_or_b64 exec, exec, s[98:99]
	s_cmp_lg_u32 s46, 1
	s_waitcnt lgkmcnt(0)
	s_barrier
	v_add_f32_e32 v2, v232, v2
	v_div_scale_f32 v3, s[24:25], v2, v2, 1.0
	v_rcp_f32_e32 v4, v3
	v_div_scale_f32 v5, vcc, 1.0, v2, 1.0
	v_fma_f32 v6, -v3, v4, 1.0
	v_fmac_f32_e32 v4, v6, v4
	v_mul_f32_e32 v6, v5, v4
	v_fma_f32 v7, -v3, v6, v5
	v_fmac_f32_e32 v6, v7, v4
	v_fma_f32 v3, -v3, v6, v5
	v_div_fmas_f32 v3, v3, v4, v6
	v_div_fixup_f32 v2, v3, v2, 1.0
	s_cbranch_scc1 .LBB0_503
	s_lshl_b32 s1, s22, 14
	s_add_i32 s1, s1, 0
	v_pk_mul_f32 v[6:7], v[66:67], v[2:3] op_sel_hi:[1,0]
	v_pk_mul_f32 v[4:5], v[64:65], v[2:3] op_sel_hi:[1,0]
	v_lshl_add_u32 v3, v203, 4, s1
	ds_write_b128 v3, v[4:7]
	v_pk_mul_f32 v[6:7], v[70:71], v[2:3] op_sel_hi:[1,0]
	v_pk_mul_f32 v[4:5], v[68:69], v[2:3] op_sel_hi:[1,0]
	ds_write_b128 v3, v[4:7] offset:1024
	v_pk_mul_f32 v[6:7], v[74:75], v[2:3] op_sel_hi:[1,0]
	v_pk_mul_f32 v[4:5], v[72:73], v[2:3] op_sel_hi:[1,0]
	ds_write_b128 v3, v[4:7] offset:2048
	v_pk_mul_f32 v[6:7], v[78:79], v[2:3] op_sel_hi:[1,0]
	v_pk_mul_f32 v[4:5], v[76:77], v[2:3] op_sel_hi:[1,0]
	ds_write_b128 v3, v[4:7] offset:3072
	v_pk_mul_f32 v[6:7], v[50:51], v[2:3] op_sel_hi:[1,0]
	v_pk_mul_f32 v[4:5], v[48:49], v[2:3] op_sel_hi:[1,0]
	ds_write_b128 v3, v[4:7] offset:4096
	v_pk_mul_f32 v[6:7], v[54:55], v[2:3] op_sel_hi:[1,0]
	v_pk_mul_f32 v[4:5], v[52:53], v[2:3] op_sel_hi:[1,0]
	ds_write_b128 v3, v[4:7] offset:5120
	v_pk_mul_f32 v[6:7], v[58:59], v[2:3] op_sel_hi:[1,0]
	v_pk_mul_f32 v[4:5], v[56:57], v[2:3] op_sel_hi:[1,0]
	ds_write_b128 v3, v[4:7] offset:6144
	v_pk_mul_f32 v[6:7], v[62:63], v[2:3] op_sel_hi:[1,0]
	v_pk_mul_f32 v[4:5], v[60:61], v[2:3] op_sel_hi:[1,0]
	ds_write_b128 v3, v[4:7] offset:7168
	v_pk_mul_f32 v[6:7], v[34:35], v[2:3] op_sel_hi:[1,0]
	v_pk_mul_f32 v[4:5], v[32:33], v[2:3] op_sel_hi:[1,0]
	ds_write_b128 v3, v[4:7] offset:8192
	v_pk_mul_f32 v[6:7], v[38:39], v[2:3] op_sel_hi:[1,0]
	v_pk_mul_f32 v[4:5], v[36:37], v[2:3] op_sel_hi:[1,0]
	ds_write_b128 v3, v[4:7] offset:9216
	v_pk_mul_f32 v[6:7], v[42:43], v[2:3] op_sel_hi:[1,0]
	v_pk_mul_f32 v[4:5], v[40:41], v[2:3] op_sel_hi:[1,0]
	ds_write_b128 v3, v[4:7] offset:10240
	v_pk_mul_f32 v[6:7], v[46:47], v[2:3] op_sel_hi:[1,0]
	v_pk_mul_f32 v[4:5], v[44:45], v[2:3] op_sel_hi:[1,0]
	ds_write_b128 v3, v[4:7] offset:11264
	v_pk_mul_f32 v[6:7], v[18:19], v[2:3] op_sel_hi:[1,0]
	v_pk_mul_f32 v[4:5], v[16:17], v[2:3] op_sel_hi:[1,0]
	ds_write_b128 v3, v[4:7] offset:12288
	v_pk_mul_f32 v[6:7], v[22:23], v[2:3] op_sel_hi:[1,0]
	v_pk_mul_f32 v[4:5], v[20:21], v[2:3] op_sel_hi:[1,0]
	ds_write_b128 v3, v[4:7] offset:13312
	v_pk_mul_f32 v[6:7], v[26:27], v[2:3] op_sel_hi:[1,0]
	v_pk_mul_f32 v[4:5], v[24:25], v[2:3] op_sel_hi:[1,0]
	ds_write_b128 v3, v[4:7] offset:14336
	v_pk_mul_f32 v[6:7], v[30:31], v[2:3] op_sel_hi:[1,0]
	v_pk_mul_f32 v[4:5], v[28:29], v[2:3] op_sel_hi:[1,0]
	ds_write_b128 v3, v[4:7] offset:15360

.LBB0_510:
	s_mov_b32 s67, s73
	s_lshl_b64 s[0:1], s[66:67], 2
	v_readlane_b32 s12, v253, 36
	s_add_u32 s0, s12, s0
	v_readlane_b32 s12, v253, 37
	s_mul_i32 s72, s66, 0x140000
	s_addc_u32 s1, s12, s1
	s_lshl_b64 s[22:23], s[72:73], 1
	v_readlane_b32 s12, v253, 38
	s_add_u32 s20, s12, s22
	v_readlane_b32 s12, v253, 39
	s_addc_u32 s21, s12, s23
	v_readlane_b32 s12, v253, 40
	s_add_u32 s22, s12, s22
	v_readlane_b32 s12, v253, 41
	s_addc_u32 s23, s12, s23
	v_mov_b32_e32 v223, -1
	s_branch .LBB0_513

.LBB0_513:
	v_mov_b32_e32 v0, v204
	s_barrier
	s_nop 0
	v_cmp_eq_u32_e32 vcc, 0, v0
	s_and_saveexec_b64 s[36:37], vcc
	s_cbranch_execz .LBB0_517
	s_waitcnt vmcnt(0)
	v_readfirstlane_b32 s19, v223
	v_mov_b32_e32 v223, -1
	v_mov_b32_e32 v0, 0
	s_cmp_eq_u32 s19, -1
	s_cbranch_scc0 .Lpfm_have
	s_mov_b64 s[42:43], exec
	v_mbcnt_lo_u32_b32 v0, s42, 0
	v_mbcnt_hi_u32_b32 v0, s43, v0
	v_cmp_eq_u32_e32 vcc, 0, v0
	s_and_saveexec_b64 s[38:39], vcc
	s_cbranch_execz .LBB0_516
	s_bcnt1_i32_b64 s19, s[42:43]
	v_mov_b32_e32 v2, s19
	global_atomic_add v2, v1, v2, s[0:1] sc0

.LBB0_540:
	v_cmp_lt_i32_e32 vcc, v209, v206
	s_waitcnt vmcnt(0)
	s_waitcnt lgkmcnt(0)
	s_barrier
	v_cndmask_b32_e32 v0, v205, v209, vcc
	v_cmp_eq_u32_e32 vcc, 0, v204
	s_and_saveexec_b64 s[98:99], vcc
	s_cbranch_execz .Lpfm_skip
	v_mov_b32_e32 v223, 1
	global_atomic_add v223, v1, v223, s[0:1] sc0
.Lpfm_skip:
	s_or_b64 exec, exec, s[98:99]
	v_lshlrev_b32_e32 v0, 2, v0
	ds_bpermute_b32 v66, v0, v157
	s_andn2_b64 vcc, exec, s[38:39]
	s_waitcnt lgkmcnt(0)
	s_cbranch_vccnz .LBB0_511
	v_lshlrev_b64 v[68:69], 11, v[146:147]
	v_lshl_add_u64 v[68:69], s[36:37], 0, v[68:69]
	v_lshlrev_b32_e32 v0, 3, v156
	v_lshl_add_u64 v[68:69], v[68:69], 0, v[0:1]
	v_add_f32_e32 v0, v157, v66
	v_div_scale_f32 v66, s[24:25], v0, v0, 1.0
	v_rcp_f32_e32 v67, v66
	s_nop 0
	v_fma_f32 v70, -v66, v67, 1.0
	v_fmac_f32_e32 v67, v70, v67
	v_div_scale_f32 v70, vcc, 1.0, v0, 1.0
	v_mul_f32_e32 v71, v70, v67
	v_fma_f32 v72, -v66, v71, v70
	v_fmac_f32_e32 v71, v72, v67
	v_fma_f32 v66, -v66, v71, v70
	v_div_fmas_f32 v66, v66, v67, v71
	v_div_fixup_f32 v0, v66, v0, 1.0
	v_pk_mul_f32 v[52:53], v[52:53], v[0:1] op_sel_hi:[1,0]
	v_pk_mul_f32 v[50:51], v[50:51], v[0:1] op_sel_hi:[1,0]
	v_pk_mul_f32 v[36:37], v[36:37], v[0:1] op_sel_hi:[1,0]
	v_pk_mul_f32 v[34:35], v[34:35], v[0:1] op_sel_hi:[1,0]
	v_pk_mul_f32 v[20:21], v[20:21], v[0:1] op_sel_hi:[1,0]
	v_pk_mul_f32 v[18:19], v[18:19], v[0:1] op_sel_hi:[1,0]
	v_pk_mul_f32 v[4:5], v[4:5], v[0:1] op_sel_hi:[1,0]
	v_pk_mul_f32 v[2:3], v[2:3], v[0:1] op_sel_hi:[1,0]
	v_cvt_pk_bf16_f32 v50, v50, v51
	v_cvt_pk_bf16_f32 v51, v52, v53
	v_cvt_pk_bf16_f32 v34, v34, v35
	v_cvt_pk_bf16_f32 v35, v36, v37
	v_cvt_pk_bf16_f32 v18, v18, v19
	v_cvt_pk_bf16_f32 v19, v20, v21
	v_cvt_pk_bf16_f32 v2, v2, v3
	v_cvt_pk_bf16_f32 v3, v4, v5
	global_store_dwordx2 v[68:69], v[50:51], off
	v_pk_mul_f32 v[50:51], v[56:57], v[0:1] op_sel_hi:[1,0]
	v_pk_mul_f32 v[52:53], v[54:55], v[0:1] op_sel_hi:[1,0]
	global_store_dwordx2 v[68:69], v[34:35], off offset:64
	v_pk_mul_f32 v[34:35], v[40:41], v[0:1] op_sel_hi:[1,0]
	v_pk_mul_f32 v[36:37], v[38:39], v[0:1] op_sel_hi:[1,0]
	global_store_dwordx2 v[68:69], v[18:19], off offset:128
	v_pk_mul_f32 v[18:19], v[24:25], v[0:1] op_sel_hi:[1,0]
	v_pk_mul_f32 v[20:21], v[22:23], v[0:1] op_sel_hi:[1,0]
	global_store_dwordx2 v[68:69], v[2:3], off offset:192
	v_pk_mul_f32 v[2:3], v[8:9], v[0:1] op_sel_hi:[1,0]
	v_pk_mul_f32 v[4:5], v[6:7], v[0:1] op_sel_hi:[1,0]
	v_cvt_pk_bf16_f32 v52, v52, v53
	v_cvt_pk_bf16_f32 v53, v50, v51
	v_cvt_pk_bf16_f32 v36, v36, v37
	v_cvt_pk_bf16_f32 v37, v34, v35
	v_cvt_pk_bf16_f32 v20, v20, v21
	v_cvt_pk_bf16_f32 v21, v18, v19
	v_cvt_pk_bf16_f32 v4, v4, v5
	v_cvt_pk_bf16_f32 v5, v2, v3
	global_store_dwordx2 v[68:69], v[52:53], off offset:16
	v_pk_mul_f32 v[50:51], v[60:61], v[0:1] op_sel_hi:[1,0]
	v_pk_mul_f32 v[52:53], v[58:59], v[0:1] op_sel_hi:[1,0]
	global_store_dwordx2 v[68:69], v[36:37], off offset:80
	v_pk_mul_f32 v[34:35], v[44:45], v[0:1] op_sel_hi:[1,0]
	v_pk_mul_f32 v[36:37], v[42:43], v[0:1] op_sel_hi:[1,0]
	global_store_dwordx2 v[68:69], v[20:21], off offset:144
	v_pk_mul_f32 v[18:19], v[28:29], v[0:1] op_sel_hi:[1,0]
	v_pk_mul_f32 v[20:21], v[26:27], v[0:1] op_sel_hi:[1,0]
	global_store_dwordx2 v[68:69], v[4:5], off offset:208
	v_pk_mul_f32 v[2:3], v[12:13], v[0:1] op_sel_hi:[1,0]
	v_pk_mul_f32 v[4:5], v[10:11], v[0:1] op_sel_hi:[1,0]
	v_cvt_pk_bf16_f32 v52, v52, v53
	v_cvt_pk_bf16_f32 v53, v50, v51
	v_cvt_pk_bf16_f32 v36, v36, v37
	v_cvt_pk_bf16_f32 v37, v34, v35
	v_cvt_pk_bf16_f32 v20, v20, v21
	v_cvt_pk_bf16_f32 v21, v18, v19
	v_cvt_pk_bf16_f32 v4, v4, v5
	v_cvt_pk_bf16_f32 v5, v2, v3
	global_store_dwordx2 v[68:69], v[52:53], off offset:32
	v_pk_mul_f32 v[50:51], v[64:65], v[0:1] op_sel_hi:[1,0]
	v_pk_mul_f32 v[52:53], v[62:63], v[0:1] op_sel_hi:[1,0]
	global_store_dwordx2 v[68:69], v[36:37], off offset:96
	v_pk_mul_f32 v[34:35], v[48:49], v[0:1] op_sel_hi:[1,0]
	v_pk_mul_f32 v[36:37], v[46:47], v[0:1] op_sel_hi:[1,0]
	global_store_dwordx2 v[68:69], v[20:21], off offset:160
	v_pk_mul_f32 v[18:19], v[32:33], v[0:1] op_sel_hi:[1,0]
	v_pk_mul_f32 v[20:21], v[30:31], v[0:1] op_sel_hi:[1,0]
	global_store_dwordx2 v[68:69], v[4:5], off offset:224
	v_pk_mul_f32 v[2:3], v[16:17], v[0:1] op_sel_hi:[1,0]
	v_pk_mul_f32 v[4:5], v[14:15], v[0:1] op_sel_hi:[1,0]
	v_cvt_pk_bf16_f32 v52, v52, v53
	v_cvt_pk_bf16_f32 v53, v50, v51
	v_cvt_pk_bf16_f32 v36, v36, v37
	v_cvt_pk_bf16_f32 v37, v34, v35
	v_cvt_pk_bf16_f32 v20, v20, v21
	v_cvt_pk_bf16_f32 v21, v18, v19
	v_cvt_pk_bf16_f32 v4, v4, v5
	v_cvt_pk_bf16_f32 v5, v2, v3
	global_store_dwordx2 v[68:69], v[52:53], off offset:48
	global_store_dwordx2 v[68:69], v[36:37], off offset:112
	global_store_dwordx2 v[68:69], v[20:21], off offset:176
	global_store_dwordx2 v[68:69], v[4:5], off offset:240
	s_branch .LBB0_511
